# pool mixer: the four pool_scale loads of an item hoisted and issued together (were four serialised round trips)
# baseline (speedup 1.0000x reference)
.LBB0_207:
	s_waitcnt lgkmcnt(0)
	s_barrier
	v_lshlrev_b32_e32 v84, 2, v15
	v_mov_b32_e32 v85, 0
	v_lshl_add_u64 v[86:87], v[28:29], 0, v[84:85]
	global_load_dwordx4 v[60:63], v[86:87], off
	global_load_dwordx4 v[64:67], v[86:87], off offset:64
	global_load_dwordx4 v[76:79], v[86:87], off offset:128
	global_load_dwordx4 v[80:83], v[86:87], off offset:192
	ds_read_b128 v[2:5], v40 offset:20800
	ds_read_b128 v[6:9], v41 offset:30016
	ds_read_b128 v[10:13], v41 offset:32320
	ds_read_b128 v[16:19], v41 offset:34624
	ds_read_b128 v[48:51], v41 offset:36928
	s_waitcnt lgkmcnt(3)
	v_mfma_f32_16x16x32_bf16 v[6:9], v[6:9], v[2:5], 0
	v_lshlrev_b32_e32 v0, 2, v15
	v_readlane_b32 s0, v252, 20
	v_readlane_b32 s1, v252, 21
	s_waitcnt lgkmcnt(2)
	v_mfma_f32_16x16x32_bf16 v[10:13], v[10:13], v[2:5], 0
	v_mov_b32_e32 v31, v1
	s_waitcnt lgkmcnt(1)
	v_mfma_f32_16x16x32_bf16 v[16:19], v[16:19], v[2:5], 0
	s_waitcnt lgkmcnt(0)
	v_mfma_f32_16x16x32_bf16 v[2:5], v[48:51], v[2:5], 0
	ds_read_b128 v[48:51], v40 offset:20864
	ds_read_b128 v[52:55], v41 offset:30080
	s_waitcnt lgkmcnt(0)
	v_mfma_f32_16x16x32_bf16 v[52:55], v[52:55], v[48:51], v[6:9]
	s_nop 2
	ds_read_b128 v[6:9], v41 offset:32384
	s_waitcnt lgkmcnt(0)
	v_mfma_f32_16x16x32_bf16 v[10:13], v[6:9], v[48:51], v[10:13]
	ds_read_b128 v[6:9], v41 offset:34688
	s_waitcnt lgkmcnt(0)
	v_mfma_f32_16x16x32_bf16 v[6:9], v[6:9], v[48:51], v[16:19]
	s_nop 2
	ds_read_b128 v[16:19], v41 offset:36992
	s_waitcnt lgkmcnt(0)
	v_mfma_f32_16x16x32_bf16 v[2:5], v[16:19], v[48:51], v[2:5]
	v_lshl_add_u64 v[18:19], v[28:29], 0, v[0:1]
	v_lshlrev_b32_e32 v0, 1, v15
	v_lshl_add_u64 v[16:17], s[0:1], 0, v[0:1]
	v_or_b32_e32 v0, v14, v39
	v_cmp_gt_i32_e64 s[0:1], s37, v0
	s_nop 1
	v_cndmask_b32_e64 v14, 3, 1, s[0:1]
	v_add_u32_e32 v14, v14, v0
	v_ashrrev_i32_e32 v15, 31, v14
	v_lshlrev_b64 v[14:15], 11, v[14:15]
	v_lshl_add_u64 v[14:15], v[16:17], 0, v[14:15]
	v_lshl_add_u64 v[20:21], v[14:15], 0, v[30:31]
	v_readlane_b32 s0, v252, 7
	v_readlane_b32 s1, v252, 8
	s_waitcnt vmcnt(0)
	v_mul_f32_e32 v0, v52, v60
	v_mul_f32_e32 v14, v53, v61
	v_mul_f32_e32 v15, v54, v62
	v_mul_f32_e32 v16, v55, v63
	v_cvt_pk_bf16_f32 v14, v0, v14
	v_cvt_pk_bf16_f32 v15, v15, v16
	global_store_dwordx2 v[20:21], v[14:15], off
	v_mul_f32_e32 v0, v10, v64
	v_mul_f32_e32 v10, v11, v65
	v_mul_f32_e32 v11, v12, v66
	v_mul_f32_e32 v12, v13, v67
	v_cvt_pk_bf16_f32 v10, v0, v10
	v_cvt_pk_bf16_f32 v11, v11, v12
	global_store_dwordx2 v[20:21], v[10:11], off offset:32
	v_mul_f32_e32 v0, v6, v76
	v_mul_f32_e32 v6, v7, v77
	v_mul_f32_e32 v7, v8, v78
	v_mul_f32_e32 v8, v9, v79
	v_cvt_pk_bf16_f32 v6, v0, v6
	v_cvt_pk_bf16_f32 v7, v7, v8
	global_store_dwordx2 v[20:21], v[6:7], off offset:64
	v_mul_f32_e32 v0, v2, v80
	v_mul_f32_e32 v2, v3, v81
	v_mul_f32_e32 v3, v4, v82
	v_mul_f32_e32 v4, v5, v83
	v_cvt_pk_bf16_f32 v2, v0, v2
	v_cvt_pk_bf16_f32 v3, v3, v4
	global_store_dwordx2 v[20:21], v[2:3], off offset:96
	s_barrier
	s_load_dword s0, s[0:1], 0x10
	s_waitcnt lgkmcnt(0)
	s_lshr_b32 s0, s0, 16
	s_cmp_lg_u32 s0, 0
	s_cselect_b64 s[0:1], -1, 0
	s_cmp_lg_u64 s[0:1], 0
	v_readlane_b32 s0, v252, 2
	s_addc_u32 s0, s0, 0
	s_lshl_b32 s0, s0, 1
	s_add_i32 s17, s0, s17
	s_cmp_ge_i32 s17, s16
	v_readlane_b32 s1, v252, 3
	s_cbranch_scc1 .LBB0_232
